# s_setprio 2 on the chain waves during the state-chain stage of the output pass
# speedup vs baseline: 1.0345x; 1.0006x over previous
.Lal_skip_b:
	s_waitcnt lgkmcnt(0)
	s_barrier
	s_andn2_b64 vcc, exec, s[8:9]
	s_cbranch_vccnz .LBB0_1106
	s_setprio 2
	v_lshlrev_b32_e32 v80, 1, v0
	v_add_u32_e32 v46, v66, v80
	v_add_u32_e32 v47, 0x4000, v46
	ds_read2_b64 v[34:37], v47 offset0:32 offset1:34
	v_cvt_pk_bf16_f32 v38, v18, v19
	v_cvt_pk_bf16_f32 v39, v20, v21
	v_cvt_pk_bf16_f32 v40, v22, v23
	v_cvt_pk_bf16_f32 v41, v24, v25
	ds_read2_b64 v[42:45], v47 offset0:36 offset1:38
	v_lshlrev_b32_e32 v48, 3, v51
	v_cvt_pk_bf16_f32 v72, v26, v27
	v_cvt_pk_bf16_f32 v73, v28, v29
	s_waitcnt lgkmcnt(1)
	v_mfma_f32_32x32x16_bf16 v[50:65], v[34:37], v[38:41], 0
	v_cvt_pk_bf16_f32 v74, v30, v31
	v_cvt_pk_bf16_f32 v75, v32, v33
	ds_read2_b64 v[34:37], v47 offset0:40 offset1:42
	v_cvt_pk_bf16_f32 v76, v2, v3
	v_cvt_pk_bf16_f32 v77, v4, v5
	v_cvt_pk_bf16_f32 v78, v6, v7
	v_cvt_pk_bf16_f32 v79, v8, v9
	s_waitcnt lgkmcnt(1)
	v_mfma_f32_32x32x16_bf16 v[50:65], v[42:45], v[72:75], v[50:65]
	ds_read2_b64 v[42:45], v47 offset0:44 offset1:46
	v_cvt_pk_bf16_f32 v172, v10, v11
	v_cvt_pk_bf16_f32 v173, v12, v13
	v_cvt_pk_bf16_f32 v174, v14, v15
	v_cvt_pk_bf16_f32 v175, v16, v17
	v_mov_b32_e32 v49, s92
	v_bitop3_b32 v47, v48, v141, 24 bitop3:0x78
	s_waitcnt lgkmcnt(1)
	v_mfma_f32_32x32x16_bf16 v[50:65], v[34:37], v[76:79], v[50:65]
	v_lshlrev_b32_e32 v34, 6, v70
	v_sub_u32_e32 v177, v66, v34
	v_lshl_add_u32 v70, v48, 1, v177
	ds_read_b128 v[34:37], v70 offset:50624
	v_mad_u32_u24 v49, v71, s77, v49
	v_lshlrev_b32_e32 v207, 1, v47
	v_and_b32_e32 v145, 24, v141
	s_waitcnt lgkmcnt(1)
	v_mfma_f32_32x32x16_bf16 v[50:65], v[42:45], v[172:175], v[50:65]
	v_add_u32_e32 v42, v49, v207
	ds_read_b128 v[130:133], v42 offset:45440
	v_bitop3_b32 v67, v48, v145, 16 bitop3:0x36
	v_lshlrev_b32_e32 v212, 1, v67
	v_add_u32_e32 v71, 0x5000, v46
	v_add_u32_e32 v47, v49, v212
	ds_read_b128 v[42:45], v70 offset:50656
	ds_read_b128 v[126:129], v47 offset:45440
	s_waitcnt lgkmcnt(2)
	v_mfma_f32_32x32x16_bf16 v[50:65], v[34:37], v[130:133], v[50:65]
	ds_read2_b64 v[34:37], v71 offset0:96 offset1:98
	ds_read2_b64 v[66:69], v71 offset0:100 offset1:102
	ds_read2_b64 v[178:181], v71 offset0:104 offset1:106
	ds_read2_b64 v[182:185], v71 offset0:108 offset1:110
	ds_read_b128 v[186:189], v70 offset:55744
	ds_read_b128 v[190:193], v70 offset:55776
	v_lshlrev_b32_e32 v81, 2, v0
	s_sub_i32 s58, s93, 32
	s_add_i32 s59, s94, 32
	s_and_b64 s[12:13], s[10:11], exec
	s_waitcnt lgkmcnt(6)
	v_mfma_f32_32x32x16_bf16 v[50:65], v[42:45], v[126:129], v[50:65]
	s_cselect_b32 s12, s58, s59
	s_add_i32 s12, s12, s87
	s_waitcnt lgkmcnt(5)
	v_mfma_f32_32x32x16_bf16 v[34:49], v[34:37], v[38:41], 0
	s_nop 7
	v_cvt_pk_bf16_f32 v50, v50, v51
	v_cvt_pk_bf16_f32 v51, v52, v53
	v_cvt_pk_bf16_f32 v52, v54, v55
	v_cvt_pk_bf16_f32 v53, v56, v57
	s_waitcnt lgkmcnt(4)
	v_mfma_f32_32x32x16_bf16 v[34:49], v[66:69], v[72:75], v[34:49]
	ds_read_b128 v[66:69], v81 offset:60928
	ds_read_b128 v[70:73], v81 offset:60960
	ds_read_b128 v[194:197], v81 offset:60864
	ds_read_b128 v[198:201], v81 offset:60896
	ds_read_b128 v[202:205], v81 offset:60992
	ds_read_b128 v[208:211], v81 offset:61024
	s_waitcnt lgkmcnt(4)
	v_pk_mul_f32 v[30:31], v[30:31], v[70:71]
	v_pk_mul_f32 v[26:27], v[26:27], v[66:67]
	v_pk_mul_f32 v[32:33], v[32:33], v[72:73]
	v_pk_mul_f32 v[28:29], v[28:29], v[68:69]
	ds_read_b128 v[66:69], v81 offset:61056
	ds_read_b128 v[70:73], v81 offset:61088
	s_waitcnt lgkmcnt(4)
	v_pk_mul_f32 v[22:23], v[22:23], v[198:199]
	v_mfma_f32_32x32x16_bf16 v[34:49], v[178:181], v[76:79], v[34:49]
	v_mul_f32_e64 v24, v24, v200
	v_mul_f32_e64 v25, v25, v201
	s_waitcnt lgkmcnt(1)
	v_mul_f32_e64 v10, v10, v66
	v_mul_f32_e64 v11, v11, v67
	s_waitcnt lgkmcnt(0)
	v_pk_mul_f32 v[14:15], v[14:15], v[70:71]
	v_pk_mul_f32 v[16:17], v[16:17], v[72:73]
	v_pk_mul_f32 v[12:13], v[12:13], v[68:69]
	v_pk_mul_f32 v[20:21], v[20:21], v[196:197]
	v_pk_mul_f32 v[18:19], v[18:19], v[194:195]
	v_mfma_f32_32x32x16_bf16 v[34:49], v[182:185], v[172:175], v[34:49]
	v_add_u32_e32 v172, v177, v80
	v_add_u32_e32 v66, 0xe000, v172
	ds_read2_b64 v[74:77], v66 offset0:120 offset1:122
	ds_read2_b64 v[54:57], v66 offset0:124 offset1:126
	v_mul_f32_e64 v6, v6, v208
	v_mul_f32_e64 v7, v7, v209
	v_pk_mul_f32 v[8:9], v[8:9], v[210:211]
	v_pk_mul_f32 v[4:5], v[4:5], v[204:205]
	s_waitcnt lgkmcnt(1)
	v_mfma_f32_32x32x16_bf16 v[66:81], v[74:77], v[50:53], 0
	v_cvt_pk_bf16_f32 v50, v58, v59
	v_cvt_pk_bf16_f32 v51, v60, v61
	v_cvt_pk_bf16_f32 v52, v62, v63
	v_cvt_pk_bf16_f32 v53, v64, v65
	v_add_u32_e32 v62, v177, v212
	v_pk_mul_f32 v[2:3], v[2:3], v[202:203]
	s_waitcnt lgkmcnt(0)
	v_mfma_f32_32x32x16_bf16 v[66:81], v[54:57], v[50:53], v[66:81]
	v_add_u32_e32 v54, v177, v207
	ds_read_b128 v[50:53], v54 offset:40256
	ds_read_b128 v[54:57], v54 offset:42880
	ds_read_b128 v[58:61], v62 offset:40256
	ds_read_b128 v[62:65], v62 offset:42880
	s_nop 6
	v_cvt_pk_bf16_f32 v66, v66, v67
	v_mfma_f32_32x32x16_bf16 v[34:49], v[186:189], v[130:133], v[34:49]
	v_cvt_pk_bf16_f32 v67, v68, v69
	v_cvt_pk_bf16_f32 v68, v70, v71
	v_cvt_pk_bf16_f32 v69, v72, v73
	v_cvt_pk_bf16_f32 v70, v74, v75
	v_cvt_pk_bf16_f32 v72, v78, v79
	v_add_u32_e32 v78, 0xc800, v172
	v_lshl_add_u32 v74, v145, 1, v172
	s_waitcnt lgkmcnt(3)
	v_mfma_f32_32x32x16_bf16 v[18:33], v[50:53], v[130:133], v[18:33]
	v_bitop3_b32 v50, v141, 8, 24 bitop3:0x6c
	v_lshl_add_u32 v75, v50, 1, v172
	v_bitop3_b32 v50, v141, 16, 24 bitop3:0x6c
	v_lshl_add_u32 v145, v50, 1, v172
	ds_read2_b64 v[50:53], v78 offset0:248 offset1:250
	v_cvt_pk_bf16_f32 v71, v76, v77
	v_cvt_pk_bf16_f32 v73, v80, v81
	v_mfma_f32_32x32x16_bf16 v[34:49], v[190:193], v[126:129], v[34:49]
	s_waitcnt lgkmcnt(0)
	v_mfma_f32_32x32x16_bf16 v[34:49], v[50:53], v[66:69], v[34:49]
	v_mfma_f32_32x32x16_bf16 v[18:33], v[58:61], v[126:129], v[18:33]
	v_bitop3_b32 v58, v141, 24, v141 bitop3:0xc
	v_lshl_add_u32 v141, v58, 1, v172
	ds_read_b64 v[58:59], v74 offset:35072
	ds_read_b64 v[60:61], v75 offset:35072
	ds_read_b64 v[76:77], v75 offset:37696
	ds_read_b64 v[74:75], v74 offset:37696
	ds_read2_b64 v[78:81], v78 offset0:252 offset1:254
	ds_read_b64 v[50:51], v145 offset:35072
	ds_read_b64 v[52:53], v141 offset:35072
	ds_read_b64 v[174:175], v141 offset:37696
	ds_read_b64 v[172:173], v145 offset:37696
	v_xor_b32_e32 v141, 31, v0
	v_cndmask_b32_e64 v141, v141, v0, s[10:11]
	v_mov_b32_e32 v145, v1
	s_waitcnt lgkmcnt(4)
	v_mfma_f32_32x32x16_bf16 v[34:49], v[78:81], v[70:73], v[34:49]
	v_or_b32_e32 v78, s12, v141
	v_lshl_add_u32 v78, v78, 12, v144
	s_movk_i32 s13, 0x1000
	s_and_b64 vcc, exec, s[10:11]
	s_cselect_b32 s13, s13, 0xfffff000
	v_mfma_f32_32x32x16_bf16 v[2:17], v[54:57], v[130:133], v[2:17]
	s_cbranch_vccnz .Lys_fwd
	s_nop 6
	s_waitcnt vmcnt(0)
	v_add_f32_e32 v34, v34, v213
	global_store_dword v78, v34, s[56:57]
	v_mad_i32_i24 v80, s13, 1, v78
	v_add_f32_e32 v35, v35, v214
	global_store_dword v80, v35, s[56:57]
	v_mad_i32_i24 v81, s13, 2, v78
	v_add_f32_e32 v36, v36, v215
	global_store_dword v81, v36, s[56:57]
	v_mad_i32_i24 v79, s13, 3, v78
	v_add_f32_e32 v37, v37, v216
	global_store_dword v79, v37, s[56:57]
	v_mad_i32_i24 v80, s13, 8, v78
	v_add_f32_e32 v38, v38, v217
	global_store_dword v80, v38, s[56:57]
	v_mad_i32_i24 v81, s13, 9, v78
	v_add_f32_e32 v39, v39, v218
	global_store_dword v81, v39, s[56:57]
	v_mad_i32_i24 v79, s13, 10, v78
	v_add_f32_e32 v40, v40, v219
	global_store_dword v79, v40, s[56:57]
	v_mad_i32_i24 v80, s13, 11, v78
	v_add_f32_e32 v41, v41, v220
	global_store_dword v80, v41, s[56:57]
	v_mad_i32_i24 v81, s13, 16, v78
	v_add_f32_e32 v42, v42, v221
	global_store_dword v81, v42, s[56:57]
	v_mad_i32_i24 v79, s13, 17, v78
	v_add_f32_e32 v43, v43, v222
	global_store_dword v79, v43, s[56:57]
	v_mad_i32_i24 v80, s13, 18, v78
	v_add_f32_e32 v44, v44, v223
	global_store_dword v80, v44, s[56:57]
	v_mad_i32_i24 v81, s13, 19, v78
	v_add_f32_e32 v45, v45, v224
	global_store_dword v81, v45, s[56:57]
	v_mad_i32_i24 v79, s13, 24, v78
	v_add_f32_e32 v46, v46, v225
	global_store_dword v79, v46, s[56:57]
	v_mad_i32_i24 v80, s13, 25, v78
	v_add_f32_e32 v47, v47, v226
	global_store_dword v80, v47, s[56:57]
	v_mad_i32_i24 v81, s13, 26, v78
	v_add_f32_e32 v48, v48, v227
	global_store_dword v81, v48, s[56:57]
	v_mad_i32_i24 v79, s13, 27, v78
	v_add_f32_e32 v49, v49, v228
	global_store_dword v79, v49, s[56:57]
	s_branch .Lys_join

.Lys_join:
	v_mfma_f32_32x32x16_bf16 v[2:17], v[62:65], v[126:129], v[2:17]
	v_mfma_f32_32x32x16_bf16 v[18:33], v[58:61], v[66:69], v[18:33]
	v_mfma_f32_32x32x16_bf16 v[2:17], v[74:77], v[66:69], v[2:17]
	s_waitcnt lgkmcnt(2)
	v_mfma_f32_32x32x16_bf16 v[18:33], v[50:53], v[70:73], v[18:33]
	s_waitcnt lgkmcnt(0)
	v_mfma_f32_32x32x16_bf16 v[2:17], v[172:175], v[70:73], v[2:17]
	s_setprio 0
	s_branch .LBB0_1106

.Lal_skip_c:
	s_waitcnt lgkmcnt(0)
	s_barrier
	s_andn2_b64 vcc, exec, s[8:9]
	s_cbranch_vccnz .LBB0_1235
	s_setprio 2
	v_lshlrev_b32_e32 v80, 1, v0
	v_add_u32_e32 v46, v66, v80
	v_add_u32_e32 v47, 0x4000, v46
	ds_read2_b64 v[34:37], v47 offset0:32 offset1:34
	v_cvt_pk_bf16_f32 v38, v18, v19
	v_cvt_pk_bf16_f32 v39, v20, v21
	v_cvt_pk_bf16_f32 v40, v22, v23
	v_cvt_pk_bf16_f32 v41, v24, v25
	ds_read2_b64 v[42:45], v47 offset0:36 offset1:38
	v_lshlrev_b32_e32 v48, 3, v51
	v_cvt_pk_bf16_f32 v72, v26, v27
	v_cvt_pk_bf16_f32 v73, v28, v29
	s_waitcnt lgkmcnt(1)
	v_mfma_f32_32x32x16_bf16 v[50:65], v[34:37], v[38:41], 0
	v_cvt_pk_bf16_f32 v74, v30, v31
	v_cvt_pk_bf16_f32 v75, v32, v33
	ds_read2_b64 v[34:37], v47 offset0:40 offset1:42
	v_cvt_pk_bf16_f32 v76, v2, v3
	v_cvt_pk_bf16_f32 v77, v4, v5
	v_cvt_pk_bf16_f32 v78, v6, v7
	v_cvt_pk_bf16_f32 v79, v8, v9
	s_waitcnt lgkmcnt(1)
	v_mfma_f32_32x32x16_bf16 v[50:65], v[42:45], v[72:75], v[50:65]
	ds_read2_b64 v[42:45], v47 offset0:44 offset1:46
	v_cvt_pk_bf16_f32 v172, v10, v11
	v_cvt_pk_bf16_f32 v173, v12, v13
	v_cvt_pk_bf16_f32 v174, v14, v15
	v_cvt_pk_bf16_f32 v175, v16, v17
	v_mov_b32_e32 v49, s88
	v_bitop3_b32 v47, v48, v141, 24 bitop3:0x78
	s_waitcnt lgkmcnt(1)
	v_mfma_f32_32x32x16_bf16 v[50:65], v[34:37], v[76:79], v[50:65]
	v_lshlrev_b32_e32 v34, 6, v70
	v_sub_u32_e32 v177, v66, v34
	v_lshl_add_u32 v70, v48, 1, v177
	ds_read_b128 v[34:37], v70 offset:50624
	v_mad_u32_u24 v49, v71, s77, v49
	v_lshlrev_b32_e32 v207, 1, v47
	v_and_b32_e32 v145, 24, v141
	s_waitcnt lgkmcnt(1)
	v_mfma_f32_32x32x16_bf16 v[50:65], v[42:45], v[172:175], v[50:65]
	v_add_u32_e32 v42, v49, v207
	ds_read_b128 v[130:133], v42 offset:45440
	v_bitop3_b32 v67, v48, v145, 16 bitop3:0x36
	v_lshlrev_b32_e32 v212, 1, v67
	v_add_u32_e32 v71, 0x5000, v46
	v_add_u32_e32 v47, v49, v212
	ds_read_b128 v[42:45], v70 offset:50656
	ds_read_b128 v[126:129], v47 offset:45440
	s_waitcnt lgkmcnt(2)
	v_mfma_f32_32x32x16_bf16 v[50:65], v[34:37], v[130:133], v[50:65]
	ds_read2_b64 v[34:37], v71 offset0:96 offset1:98
	ds_read2_b64 v[66:69], v71 offset0:100 offset1:102
	ds_read2_b64 v[178:181], v71 offset0:104 offset1:106
	ds_read2_b64 v[182:185], v71 offset0:108 offset1:110
	ds_read_b128 v[186:189], v70 offset:55744
	ds_read_b128 v[190:193], v70 offset:55776
	v_lshlrev_b32_e32 v81, 2, v0
	s_add_i32 s58, s89, 32
	s_and_b64 s[12:13], s[10:11], exec
	s_cselect_b32 s12, s91, s58
	s_waitcnt lgkmcnt(6)
	v_mfma_f32_32x32x16_bf16 v[50:65], v[42:45], v[126:129], v[50:65]
	s_add_i32 s12, s12, s83
	s_waitcnt lgkmcnt(5)
	v_mfma_f32_32x32x16_bf16 v[34:49], v[34:37], v[38:41], 0
	s_nop 8
	v_cvt_pk_bf16_f32 v50, v50, v51
	v_cvt_pk_bf16_f32 v51, v52, v53
	v_cvt_pk_bf16_f32 v52, v54, v55
	v_cvt_pk_bf16_f32 v53, v56, v57
	s_waitcnt lgkmcnt(4)
	v_mfma_f32_32x32x16_bf16 v[34:49], v[66:69], v[72:75], v[34:49]
	ds_read_b128 v[66:69], v81 offset:60928
	ds_read_b128 v[70:73], v81 offset:60960
	ds_read_b128 v[194:197], v81 offset:60864
	ds_read_b128 v[198:201], v81 offset:60896
	ds_read_b128 v[202:205], v81 offset:60992
	ds_read_b128 v[208:211], v81 offset:61024
	s_waitcnt lgkmcnt(4)
	v_pk_mul_f32 v[30:31], v[30:31], v[70:71]
	v_pk_mul_f32 v[26:27], v[26:27], v[66:67]
	v_pk_mul_f32 v[32:33], v[32:33], v[72:73]
	v_pk_mul_f32 v[28:29], v[28:29], v[68:69]
	ds_read_b128 v[66:69], v81 offset:61056
	ds_read_b128 v[70:73], v81 offset:61088
	s_waitcnt lgkmcnt(4)
	v_pk_mul_f32 v[22:23], v[22:23], v[198:199]
	v_mfma_f32_32x32x16_bf16 v[34:49], v[178:181], v[76:79], v[34:49]
	v_mul_f32_e64 v24, v24, v200
	v_mul_f32_e64 v25, v25, v201
	s_waitcnt lgkmcnt(1)
	v_mul_f32_e64 v10, v10, v66
	v_mul_f32_e64 v11, v11, v67
	s_waitcnt lgkmcnt(0)
	v_pk_mul_f32 v[14:15], v[14:15], v[70:71]
	v_pk_mul_f32 v[16:17], v[16:17], v[72:73]
	v_pk_mul_f32 v[12:13], v[12:13], v[68:69]
	v_pk_mul_f32 v[20:21], v[20:21], v[196:197]
	v_pk_mul_f32 v[18:19], v[18:19], v[194:195]
	v_mfma_f32_32x32x16_bf16 v[34:49], v[182:185], v[172:175], v[34:49]
	v_add_u32_e32 v172, v177, v80
	v_add_u32_e32 v66, 0xe000, v172
	ds_read2_b64 v[74:77], v66 offset0:120 offset1:122
	ds_read2_b64 v[54:57], v66 offset0:124 offset1:126
	v_mul_f32_e64 v6, v6, v208
	v_mul_f32_e64 v7, v7, v209
	v_pk_mul_f32 v[8:9], v[8:9], v[210:211]
	v_pk_mul_f32 v[4:5], v[4:5], v[204:205]
	s_waitcnt lgkmcnt(1)
	v_mfma_f32_32x32x16_bf16 v[66:81], v[74:77], v[50:53], 0
	v_cvt_pk_bf16_f32 v50, v58, v59
	v_cvt_pk_bf16_f32 v51, v60, v61
	v_cvt_pk_bf16_f32 v52, v62, v63
	v_cvt_pk_bf16_f32 v53, v64, v65
	v_add_u32_e32 v62, v177, v212
	v_pk_mul_f32 v[2:3], v[2:3], v[202:203]
	s_waitcnt lgkmcnt(0)
	v_mfma_f32_32x32x16_bf16 v[66:81], v[54:57], v[50:53], v[66:81]
	v_add_u32_e32 v54, v177, v207
	ds_read_b128 v[50:53], v54 offset:40256
	ds_read_b128 v[54:57], v54 offset:42880
	ds_read_b128 v[58:61], v62 offset:40256
	ds_read_b128 v[62:65], v62 offset:42880
	s_nop 6
	v_cvt_pk_bf16_f32 v66, v66, v67
	v_mfma_f32_32x32x16_bf16 v[34:49], v[186:189], v[130:133], v[34:49]
	v_cvt_pk_bf16_f32 v67, v68, v69
	v_cvt_pk_bf16_f32 v68, v70, v71
	v_cvt_pk_bf16_f32 v69, v72, v73
	v_cvt_pk_bf16_f32 v70, v74, v75
	v_cvt_pk_bf16_f32 v72, v78, v79
	v_add_u32_e32 v78, 0xc800, v172
	v_lshl_add_u32 v74, v145, 1, v172
	s_waitcnt lgkmcnt(3)
	v_mfma_f32_32x32x16_bf16 v[18:33], v[50:53], v[130:133], v[18:33]
	v_bitop3_b32 v50, v141, 8, 24 bitop3:0x6c
	v_lshl_add_u32 v75, v50, 1, v172
	v_bitop3_b32 v50, v141, 16, 24 bitop3:0x6c
	v_lshl_add_u32 v145, v50, 1, v172
	ds_read2_b64 v[50:53], v78 offset0:248 offset1:250
	v_cvt_pk_bf16_f32 v71, v76, v77
	v_cvt_pk_bf16_f32 v73, v80, v81
	v_mfma_f32_32x32x16_bf16 v[34:49], v[190:193], v[126:129], v[34:49]
	s_waitcnt lgkmcnt(0)
	v_mfma_f32_32x32x16_bf16 v[34:49], v[50:53], v[66:69], v[34:49]
	v_mfma_f32_32x32x16_bf16 v[18:33], v[58:61], v[126:129], v[18:33]
	v_bitop3_b32 v58, v141, 24, v141 bitop3:0xc
	v_lshl_add_u32 v141, v58, 1, v172
	ds_read_b64 v[58:59], v74 offset:35072
	ds_read_b64 v[60:61], v75 offset:35072
	ds_read_b64 v[76:77], v75 offset:37696
	ds_read_b64 v[74:75], v74 offset:37696
	ds_read2_b64 v[78:81], v78 offset0:252 offset1:254
	ds_read_b64 v[50:51], v145 offset:35072
	ds_read_b64 v[52:53], v141 offset:35072
	ds_read_b64 v[174:175], v141 offset:37696
	ds_read_b64 v[172:173], v145 offset:37696
	v_xor_b32_e32 v141, 31, v0
	v_cndmask_b32_e64 v141, v141, v0, s[10:11]
	s_waitcnt lgkmcnt(4)
	v_mfma_f32_32x32x16_bf16 v[34:49], v[78:81], v[70:73], v[34:49]
	v_or_b32_e32 v78, s12, v141
	v_lshl_add_u32 v78, v78, 12, v144
	s_movk_i32 s13, 0x1000
	s_and_b64 vcc, exec, s[10:11]
	s_cselect_b32 s13, s13, 0xfffff000
	v_mfma_f32_32x32x16_bf16 v[2:17], v[54:57], v[130:133], v[2:17]
	s_cbranch_vccnz .Lys3_fwd
	s_nop 6
	s_waitcnt vmcnt(0)
	v_add_f32_e32 v34, v34, v213
	global_store_dword v78, v34, s[56:57]
	v_mad_i32_i24 v80, s13, 1, v78
	v_add_f32_e32 v35, v35, v214
	global_store_dword v80, v35, s[56:57]
	v_mad_i32_i24 v81, s13, 2, v78
	v_add_f32_e32 v36, v36, v215
	global_store_dword v81, v36, s[56:57]
	v_mad_i32_i24 v79, s13, 3, v78
	v_add_f32_e32 v37, v37, v216
	global_store_dword v79, v37, s[56:57]
	v_mad_i32_i24 v80, s13, 8, v78
	v_add_f32_e32 v38, v38, v217
	global_store_dword v80, v38, s[56:57]
	v_mad_i32_i24 v81, s13, 9, v78
	v_add_f32_e32 v39, v39, v218
	global_store_dword v81, v39, s[56:57]
	v_mad_i32_i24 v79, s13, 10, v78
	v_add_f32_e32 v40, v40, v219
	global_store_dword v79, v40, s[56:57]
	v_mad_i32_i24 v80, s13, 11, v78
	v_add_f32_e32 v41, v41, v220
	global_store_dword v80, v41, s[56:57]
	v_mad_i32_i24 v81, s13, 16, v78
	v_add_f32_e32 v42, v42, v221
	global_store_dword v81, v42, s[56:57]
	v_mad_i32_i24 v79, s13, 17, v78
	v_add_f32_e32 v43, v43, v222
	global_store_dword v79, v43, s[56:57]
	v_mad_i32_i24 v80, s13, 18, v78
	v_add_f32_e32 v44, v44, v223
	global_store_dword v80, v44, s[56:57]
	v_mad_i32_i24 v81, s13, 19, v78
	v_add_f32_e32 v45, v45, v224
	global_store_dword v81, v45, s[56:57]
	v_mad_i32_i24 v79, s13, 24, v78
	v_add_f32_e32 v46, v46, v225
	global_store_dword v79, v46, s[56:57]
	v_mad_i32_i24 v80, s13, 25, v78
	v_add_f32_e32 v47, v47, v226
	global_store_dword v80, v47, s[56:57]
	v_mad_i32_i24 v81, s13, 26, v78
	v_add_f32_e32 v48, v48, v227
	global_store_dword v81, v48, s[56:57]
	v_mad_i32_i24 v79, s13, 27, v78
	v_add_f32_e32 v49, v49, v228
	global_store_dword v79, v49, s[56:57]
	s_branch .Lys3_join
